# P2a kbar: next item's K rows prefetched during the current item's reduction
# speedup vs baseline: 1.0115x; 1.0041x over previous
; __device__ __forceinline__ int opaque_tid() { int t = threadIdx.x; asm volatile("" : "+v"(t)); return t; }
; __device__ __forceinline__ void p2a_kbar(const Args& A, char* lds, int G) {
;     const int tid = opaque_tid(); const bf16* P0 = (const bf16*)(A.ws + WS_BIG); float* kbar = (float*)(A.ws + WS_KBAR); float* red = (float*)lds;
;     for (int item = blockIdx.x; item < NB * 16 * 8; item += G) {
;         const int b = item >> 7, h = (item >> 3) & 15, n = item & 7; const int c8 = tid & 7, rg = tid >> 3;
;         float acc[8];
; #pragma unroll
;         for (int e = 0; e < 8; ++e) acc[e] = 0.f;
; #pragma unroll
;         for (int i = 0; i < 4; ++i) { const bf16x8 kv = *(const bf16x8*)(P0 + (size_t)(b * SEQL + n * 256 + rg + 64 * i) * LD0 + C0_K + h * 64 + c8 * 8);
.LBB0_592:
	s_or_b64 exec, exec, s[36:37]
	s_add_i32 s0, 0, 0x20438
	v_mov_b32_e32 v0, s0
	s_add_i32 s0, 0, 0x204d8
	v_mov_b32_e32 v4, s0
	s_waitcnt lgkmcnt(0)
	s_barrier
	ds_read2_b64 v[0:3], v0 offset1:1
	ds_read2_b64 v[4:7], v4 offset1:1
	s_mov_b32 s7, 0
	s_cmpk_gt_i32 s2, 0x3ff
	s_waitcnt lgkmcnt(0)
	v_readfirstlane_b32 s15, v1
	v_readfirstlane_b32 s14, v0
	v_readfirstlane_b32 s13, v3
	v_readfirstlane_b32 s12, v2
	v_readfirstlane_b32 s11, v5
	v_readfirstlane_b32 s10, v4
	v_readfirstlane_b32 s9, v7
	v_readfirstlane_b32 s8, v6
	v_mov_b32_e32 v2, v220
	s_cbranch_scc1 .LBB0_597
	v_ashrrev_i32_e32 v6, 3, v2
	s_movk_i32 s0, 0x104
	s_ashr_i32 s3, s2, 31
	v_mul_lo_u32 v4, v6, s0
	s_lshl_b64 s[0:1], s[2:3], 8
	v_and_b32_e32 v3, 7, v2
	s_add_u32 s0, s8, s0
	v_lshlrev_b32_e32 v0, 3, v3
	v_lshlrev_b32_e32 v9, 5, v3
	v_ashrrev_i32_e32 v3, 31, v2
	s_addc_u32 s1, s9, s1
	v_cmp_gt_i32_e64 s[4:5], 64, v2
	v_lshl_add_u32 v7, v2, 2, 0
	v_lshl_add_u64 v[2:3], v[2:3], 2, s[0:1]
	s_mov_b64 s[0:1], 0x210000
	v_add_u32_e32 v8, 0, v4
	v_lshl_add_u64 v[2:3], v[2:3], 0, s[0:1]
	s_ashr_i32 s1, s38, 31
	s_mov_b32 s0, s38
	v_mov_b32_e32 v1, 0
	s_lshl_b64 s[16:17], s[0:1], 8
	s_lshl_b32 s0, s2, 3
	s_lshl_b32 s1, s2, 8
	s_lshl_b32 s3, s38, 8
	s_lshl_b32 s20, s2, 4
	s_lshl_b32 s21, s38, 4
	s_movk_i32 s22, 0x3400
	v_mov_b64_e32 v[4:5], s[8:9]
	v_lshlrev_b32_e32 v0, 1, v0
	v_add_u32_e32 v8, v8, v9
	s_mov_b32 s23, s2
	s_and_b32 s6, s20, 0xfffff800
	s_and_b32 s18, s1, 0x700
	s_or_b32 s6, s6, s18
	v_add_u32_e32 v9, s6, v6
	s_and_b32 s6, s0, 0x3c0
	v_mad_i64_i32 v[34:35], s[18:19], v9, s22, v[4:5]
	s_lshl_b32 s6, s6, 1
	v_lshl_add_u64 v[34:35], v[34:35], 0, s[6:7]
	v_add_u32_e32 v38, 64, v9
	v_lshl_add_u64 v[34:35], v[34:35], 0, v[0:1]
	v_mad_i64_i32 v[38:39], s[18:19], v38, s22, v[4:5]
	v_add_co_u32_e32 v34, vcc, 0x1b02000, v34
	v_lshl_add_u64 v[38:39], v[38:39], 0, s[6:7]
	v_add_u32_e32 v42, 0x80, v9
	v_addc_co_u32_e32 v35, vcc, 0, v35, vcc
	v_lshl_add_u64 v[38:39], v[38:39], 0, v[0:1]
	v_mad_i64_i32 v[42:43], s[18:19], v42, s22, v[4:5]
	v_add_co_u32_e32 v38, vcc, 0x1b02000, v38
	v_lshl_add_u64 v[42:43], v[42:43], 0, s[6:7]
	v_add_u32_e32 v9, 0xc0, v9
	v_addc_co_u32_e32 v39, vcc, 0, v39, vcc
	v_lshl_add_u64 v[42:43], v[42:43], 0, v[0:1]
	v_mad_i64_i32 v[46:47], s[18:19], v9, s22, v[4:5]
	v_add_co_u32_e32 v42, vcc, 0x1b02000, v42
	v_lshl_add_u64 v[46:47], v[46:47], 0, s[6:7]
	global_load_dwordx4 v[34:37], v[34:35], off offset:1024
	v_addc_co_u32_e32 v43, vcc, 0, v43, vcc
	v_lshl_add_u64 v[46:47], v[46:47], 0, v[0:1]
	global_load_dwordx4 v[38:41], v[38:39], off offset:1024
	v_add_co_u32_e32 v46, vcc, 0x1b02000, v46
	global_load_dwordx4 v[42:45], v[42:43], off offset:1024
	s_nop 0
	v_addc_co_u32_e32 v47, vcc, 0, v47, vcc
	global_load_dwordx4 v[46:49], v[46:47], off offset:1024
	s_branch .LBB0_595

; __device__ __forceinline__ float bf2f(unsigned short h) { return __uint_as_float(((unsigned)h) << 16); }
; __device__ __forceinline__ void p2a_kbar(const Args& A, char* lds, int G) {
;     ...
; #pragma unroll
;         for (int i = 0; i < 4; ++i) { const bf16x8 kv = *(const bf16x8*)(P0 + (size_t)(b * SEQL + n * 256 + rg + 64 * i) * LD0 + C0_K + h * 64 + c8 * 8);
; #pragma unroll
;             for (int e = 0; e < 8; ++e) acc[e] += bf2f((unsigned short)kv[e]); }
;         __syncthreads();
; #pragma unroll
;         for (int e = 0; e < 8; ++e) red[rg * 65 + c8 * 8 + e] = acc[e];
;         __syncthreads();
;         if (tid < 64) { float s = 0.f; for (int r = 0; r < 64; ++r) s += red[r * 65 + tid]; kbar[(size_t)item * 64 + tid] = s * (1.f / 256.f); }
.LBB0_595:
	s_waitcnt lgkmcnt(0)
	s_barrier
	s_waitcnt vmcnt(0)
	v_mov_b32_e32 v10, v34
	v_mov_b32_e32 v11, v35
	v_mov_b32_e32 v12, v36
	v_mov_b32_e32 v13, v37
	v_mov_b32_e32 v14, v38
	v_mov_b32_e32 v15, v39
	v_mov_b32_e32 v16, v40
	v_mov_b32_e32 v17, v41
	v_mov_b32_e32 v18, v42
	v_mov_b32_e32 v19, v43
	v_mov_b32_e32 v20, v44
	v_mov_b32_e32 v21, v45
	v_mov_b32_e32 v22, v46
	v_mov_b32_e32 v23, v47
	v_mov_b32_e32 v24, v48
	v_mov_b32_e32 v25, v49
	v_and_b32_e32 v27, 0xffff0000, v10
	v_lshlrev_b32_e32 v26, 16, v10
	v_and_b32_e32 v29, 0xffff0000, v11
	v_lshlrev_b32_e32 v28, 16, v11
	v_and_b32_e32 v11, 0xffff0000, v12
	v_lshlrev_b32_e32 v10, 16, v12
	v_and_b32_e32 v31, 0xffff0000, v13
	v_lshlrev_b32_e32 v30, 16, v13
	v_pk_add_f32 v[12:13], v[26:27], 0 op_sel_hi:[1,0]
	v_and_b32_e32 v27, 0xffff0000, v14
	v_lshlrev_b32_e32 v26, 16, v14
	v_and_b32_e32 v33, 0xffff0000, v15
	v_lshlrev_b32_e32 v32, 16, v15
	v_pk_add_f32 v[10:11], v[10:11], 0 op_sel_hi:[1,0]
	v_and_b32_e32 v15, 0xffff0000, v16
	v_lshlrev_b32_e32 v14, 16, v16
	v_pk_add_f32 v[28:29], v[28:29], 0 op_sel_hi:[1,0]
	v_pk_add_f32 v[12:13], v[12:13], v[26:27]
	v_and_b32_e32 v27, 0xffff0000, v18
	v_lshlrev_b32_e32 v26, 16, v18
	v_pk_add_f32 v[10:11], v[10:11], v[14:15]
	v_and_b32_e32 v15, 0xffff0000, v20
	v_lshlrev_b32_e32 v14, 16, v20
	v_pk_add_f32 v[28:29], v[28:29], v[32:33]
	v_and_b32_e32 v33, 0xffff0000, v19
	v_lshlrev_b32_e32 v32, 16, v19
	v_pk_add_f32 v[12:13], v[12:13], v[26:27]
	v_and_b32_e32 v19, 0xffff0000, v22
	v_lshlrev_b32_e32 v18, 16, v22
	v_pk_add_f32 v[10:11], v[10:11], v[14:15]
	v_and_b32_e32 v15, 0xffff0000, v24
	v_lshlrev_b32_e32 v14, 16, v24
	v_pk_add_f32 v[26:27], v[28:29], v[32:33]
	v_and_b32_e32 v29, 0xffff0000, v23
	v_lshlrev_b32_e32 v28, 16, v23
	v_pk_add_f32 v[12:13], v[12:13], v[18:19]
	v_pk_add_f32 v[10:11], v[10:11], v[14:15]
	v_pk_add_f32 v[30:31], v[30:31], 0 op_sel_hi:[1,0]
	v_pk_add_f32 v[18:19], v[26:27], v[28:29]
	ds_write2_b32 v8, v12, v13 offset1:1
	ds_write2_b32 v8, v18, v19 offset0:2 offset1:3
	ds_write2_b32 v8, v10, v11 offset0:4 offset1:5
	v_and_b32_e32 v11, 0xffff0000, v17
	v_lshlrev_b32_e32 v10, 16, v17
	v_pk_add_f32 v[10:11], v[30:31], v[10:11]
	v_and_b32_e32 v13, 0xffff0000, v21
	v_lshlrev_b32_e32 v12, 16, v21
	v_pk_add_f32 v[10:11], v[10:11], v[12:13]
	v_and_b32_e32 v13, 0xffff0000, v25
	v_lshlrev_b32_e32 v12, 16, v25
	v_pk_add_f32 v[10:11], v[10:11], v[12:13]
	ds_write2_b32 v8, v10, v11 offset0:6 offset1:7
	s_add_i32 s98, s23, s38
	s_cmpk_lt_i32 s98, 0x400
	s_cbranch_scc0 .Lkb_nopf
	s_add_i32 s99, s20, s21
	s_add_i32 s100, s1, s3
	s_add_i32 s101, s0, s44
	s_and_b32 s6, s99, 0xfffff800
	s_and_b32 s18, s100, 0x700
	s_or_b32 s6, s6, s18
	v_add_u32_e32 v9, s6, v6
	s_and_b32 s6, s101, 0x3c0
	v_mad_i64_i32 v[34:35], s[18:19], v9, s22, v[4:5]
	s_lshl_b32 s6, s6, 1
	v_lshl_add_u64 v[34:35], v[34:35], 0, s[6:7]
	v_add_u32_e32 v38, 64, v9
	v_lshl_add_u64 v[34:35], v[34:35], 0, v[0:1]
	v_mad_i64_i32 v[38:39], s[18:19], v38, s22, v[4:5]
	v_add_co_u32_e32 v34, vcc, 0x1b02000, v34
	v_lshl_add_u64 v[38:39], v[38:39], 0, s[6:7]
	v_add_u32_e32 v42, 0x80, v9
	v_addc_co_u32_e32 v35, vcc, 0, v35, vcc
	v_lshl_add_u64 v[38:39], v[38:39], 0, v[0:1]
	v_mad_i64_i32 v[42:43], s[18:19], v42, s22, v[4:5]
	v_add_co_u32_e32 v38, vcc, 0x1b02000, v38
	v_lshl_add_u64 v[42:43], v[42:43], 0, s[6:7]
	v_add_u32_e32 v9, 0xc0, v9
	v_addc_co_u32_e32 v39, vcc, 0, v39, vcc
	v_lshl_add_u64 v[42:43], v[42:43], 0, v[0:1]
	v_mad_i64_i32 v[46:47], s[18:19], v9, s22, v[4:5]
	v_add_co_u32_e32 v42, vcc, 0x1b02000, v42
	v_lshl_add_u64 v[46:47], v[46:47], 0, s[6:7]
	global_load_dwordx4 v[34:37], v[34:35], off offset:1024
	v_addc_co_u32_e32 v43, vcc, 0, v43, vcc
	v_lshl_add_u64 v[46:47], v[46:47], 0, v[0:1]
	global_load_dwordx4 v[38:41], v[38:39], off offset:1024
	v_add_co_u32_e32 v46, vcc, 0x1b02000, v46
	global_load_dwordx4 v[42:45], v[42:43], off offset:1024
	s_nop 0
	v_addc_co_u32_e32 v47, vcc, 0, v47, vcc
	global_load_dwordx4 v[46:49], v[46:47], off offset:1024
; __device__ __forceinline__ void p2a_kbar(const Args& A, char* lds, int G) {
;     ...
;         if (tid < 64) { float s = 0.f; for (int r = 0; r < 64; ++r) s += red[r * 65 + tid]; kbar[(size_t)item * 64 + tid] = s * (1.f / 256.f); }
.Lkb_nopf:
	s_waitcnt lgkmcnt(0)
	s_barrier
	s_and_saveexec_b64 s[18:19], s[4:5]
	s_cbranch_execz .LBB0_594
	ds_read2_b32 v[10:11], v7 offset1:65
	ds_read2_b32 v[12:13], v7 offset0:130 offset1:195
	v_add_u32_e32 v9, 0x400, v7
	ds_read2_b32 v[14:15], v9 offset0:4 offset1:69
	ds_read2_b32 v[16:17], v9 offset0:134 offset1:199
	s_waitcnt lgkmcnt(3)
	v_add_f32_e32 v9, 0, v10
	v_add_f32_e32 v9, v9, v11
	s_waitcnt lgkmcnt(2)
	v_add_f32_e32 v9, v9, v12
	v_add_u32_e32 v12, 0x800, v7
	v_add_f32_e32 v9, v9, v13
	ds_read2_b32 v[10:11], v12 offset0:8 offset1:73
	s_waitcnt lgkmcnt(2)
	v_add_f32_e32 v9, v9, v14
	v_add_f32_e32 v9, v9, v15
	s_waitcnt lgkmcnt(1)
	v_add_f32_e32 v9, v9, v16
	v_add_f32_e32 v9, v9, v17
	ds_read2_b32 v[12:13], v12 offset0:138 offset1:203
	s_waitcnt lgkmcnt(1)
	v_add_f32_e32 v9, v9, v10
	v_add_u32_e32 v10, 0xc00, v7
	ds_read2_b32 v[14:15], v10 offset0:12 offset1:77
	v_add_f32_e32 v9, v9, v11
	ds_read2_b32 v[10:11], v10 offset0:142 offset1:207
	s_waitcnt lgkmcnt(2)
	v_add_f32_e32 v9, v9, v12
	v_add_f32_e32 v9, v9, v13
	s_waitcnt lgkmcnt(1)
	v_add_f32_e32 v9, v9, v14
	v_add_f32_e32 v9, v9, v15
	s_waitcnt lgkmcnt(0)
	v_add_f32_e32 v9, v9, v10
	v_add_u32_e32 v10, 0x1000, v7
	ds_read2_b32 v[12:13], v10 offset0:16 offset1:81
	v_add_f32_e32 v9, v9, v11
	ds_read2_b32 v[10:11], v10 offset0:146 offset1:211
	v_add_u32_e32 v16, 0x1400, v7
	ds_read2_b32 v[14:15], v16 offset0:20 offset1:85
	s_waitcnt lgkmcnt(2)
	v_add_f32_e32 v9, v9, v12
	v_add_f32_e32 v9, v9, v13
	s_waitcnt lgkmcnt(1)
	v_add_f32_e32 v9, v9, v10
	v_add_f32_e32 v9, v9, v11
	ds_read2_b32 v[10:11], v16 offset0:150 offset1:215
	s_waitcnt lgkmcnt(1)
	v_add_f32_e32 v9, v9, v14
	v_add_u32_e32 v14, 0x1800, v7
	ds_read2_b32 v[12:13], v14 offset0:24 offset1:89
	v_add_f32_e32 v9, v9, v15
	s_waitcnt lgkmcnt(1)
	v_add_f32_e32 v9, v9, v10
	ds_read2_b32 v[14:15], v14 offset0:154 offset1:219
	v_add_f32_e32 v9, v9, v11
	s_waitcnt lgkmcnt(1)
	v_add_f32_e32 v9, v9, v12
	v_add_u32_e32 v12, 0x1c00, v7
	ds_read2_b32 v[10:11], v12 offset0:28 offset1:93
	v_add_f32_e32 v9, v9, v13
	ds_read2_b32 v[12:13], v12 offset0:158 offset1:223
	s_waitcnt lgkmcnt(2)
	v_add_f32_e32 v9, v9, v14
	v_add_u32_e32 v16, 0x2000, v7
	v_add_f32_e32 v9, v9, v15
	ds_read2_b32 v[14:15], v16 offset0:32 offset1:97
	s_waitcnt lgkmcnt(2)
	v_add_f32_e32 v9, v9, v10
	v_add_f32_e32 v9, v9, v11
	s_waitcnt lgkmcnt(1)
	v_add_f32_e32 v9, v9, v12
	v_add_f32_e32 v9, v9, v13
	ds_read2_b32 v[10:11], v16 offset0:162 offset1:227
	s_waitcnt lgkmcnt(1)
	v_add_f32_e32 v9, v9, v14
	v_add_u32_e32 v14, 0x2400, v7
	ds_read2_b32 v[12:13], v14 offset0:36 offset1:101
	v_add_f32_e32 v9, v9, v15
	s_waitcnt lgkmcnt(1)
	v_add_f32_e32 v9, v9, v10
	ds_read2_b32 v[14:15], v14 offset0:166 offset1:231
	v_add_f32_e32 v9, v9, v11
	s_waitcnt lgkmcnt(1)
	v_add_f32_e32 v9, v9, v12
	v_add_u32_e32 v12, 0x2800, v7
	ds_read2_b32 v[10:11], v12 offset0:40 offset1:105
	v_add_f32_e32 v9, v9, v13
	ds_read2_b32 v[12:13], v12 offset0:170 offset1:235
	s_waitcnt lgkmcnt(2)
	v_add_f32_e32 v9, v9, v14
	v_add_u32_e32 v16, 0x2c00, v7
	v_add_f32_e32 v9, v9, v15
	ds_read2_b32 v[14:15], v16 offset0:44 offset1:109
	s_waitcnt lgkmcnt(2)
	v_add_f32_e32 v9, v9, v10
	v_add_f32_e32 v9, v9, v11
	s_waitcnt lgkmcnt(1)
	v_add_f32_e32 v9, v9, v12
	v_add_f32_e32 v9, v9, v13
	ds_read2_b32 v[10:11], v16 offset0:174 offset1:239
	s_waitcnt lgkmcnt(1)
	v_add_f32_e32 v9, v9, v14
	v_add_u32_e32 v14, 0x3000, v7
	ds_read2_b32 v[12:13], v14 offset0:48 offset1:113
	v_add_f32_e32 v9, v9, v15
	s_waitcnt lgkmcnt(1)
	v_add_f32_e32 v9, v9, v10
	ds_read2_b32 v[14:15], v14 offset0:178 offset1:243
	v_add_f32_e32 v9, v9, v11
	s_waitcnt lgkmcnt(1)
	v_add_f32_e32 v9, v9, v12
	v_add_u32_e32 v12, 0x3400, v7
	ds_read2_b32 v[10:11], v12 offset0:52 offset1:117
	v_add_f32_e32 v9, v9, v13
	ds_read2_b32 v[12:13], v12 offset0:182 offset1:247
	s_waitcnt lgkmcnt(2)
	v_add_f32_e32 v9, v9, v14
	v_add_u32_e32 v16, 0x3800, v7
	v_add_f32_e32 v9, v9, v15
	ds_read2_b32 v[14:15], v16 offset0:56 offset1:121
	s_waitcnt lgkmcnt(2)
	v_add_f32_e32 v9, v9, v10
	v_add_f32_e32 v9, v9, v11
	s_waitcnt lgkmcnt(1)
	v_add_f32_e32 v9, v9, v12
	v_add_f32_e32 v9, v9, v13
	ds_read2_b32 v[10:11], v16 offset0:186 offset1:251
	s_waitcnt lgkmcnt(1)
	v_add_f32_e32 v9, v9, v14
	v_add_u32_e32 v14, 0x3c00, v7
	ds_read2_b32 v[12:13], v14 offset0:60 offset1:125
	v_add_f32_e32 v9, v9, v15
	ds_read2_b32 v[14:15], v14 offset0:190 offset1:255
	s_waitcnt lgkmcnt(2)
	v_add_f32_e32 v9, v9, v10
	v_add_f32_e32 v9, v9, v11
	s_waitcnt lgkmcnt(1)
	v_add_f32_e32 v9, v9, v12
	v_add_f32_e32 v9, v9, v13
	s_waitcnt lgkmcnt(0)
	v_add_f32_e32 v9, v9, v14
	v_add_f32_e32 v9, v9, v15
	v_mul_f32_e32 v9, 0x3b800000, v9
	flat_store_dword v[2:3], v9
	s_branch .LBB0_594
